# XCD-staggered start (x * 6400 cycles) of the four out-proj GEMM phases so the epilogue memory bursts of different XCDs do not coincide
# baseline (speedup 1.0000x reference)
; #define PP load_params()
; template <int layer>
; __device__ __forceinline__ void run_layer(LAS unsigned char* lds, const XcdBarrier& xb) {
;     ...
;             xcd_barrier(xb);
;             __syncthreads();
;             { pg8::GemmSched S; S.init(T, 2048, G, blockIdx.x, ws + OFF_Z0, 2048, WOUT, 2048);
;               EpiOut<layer == 0, false> E{PP.x_prompt, PP.x_sample, PP.out, XB, RSS};
;               pg8::gemm_phase(lds, 2048, 2048, 2048, S, E); }
.LBB0_600:
	s_or_b64 exec, exec, s[4:5]
	s_mov_b64 s[0:1], s[92:93]
	s_barrier
	s_barrier
	s_and_b32 s98, s33, 7
.Lstag0_loop:
	s_cmp_eq_u32 s98, 0
	s_cbranch_scc1 .Lstag0_done
	s_sleep 100
	s_sub_u32 s98, s98, 1
	s_branch .Lstag0_loop
.Lstag0_done:
	s_load_dwordx2 s[44:45], s[0:1], 0x0
	s_mov_b64 s[0:1], s[92:93]
	s_load_dwordx2 s[10:11], s[0:1], 0x8
	s_mov_b64 s[0:1], s[92:93]
	v_cndmask_b32_e64 v0, 0, 1, s[6:7]
	v_cmp_ne_u32_e64 s[0:1], 1, v0
	v_mov_b32_e32 v8, v254
	s_andn2_b64 vcc, exec, s[6:7]
	v_writelane_b32 v255, s0, 24
	v_readfirstlane_b32 s8, v8
	s_nop 0
	v_writelane_b32 v255, s1, 25
	s_cbranch_vccnz .LBB0_606
	s_ashr_i32 s0, s33, 31
	s_lshr_b32 s0, s0, 29
	s_add_i32 s0, s33, s0
	s_and_b32 s1, s0, -8
	s_sub_i32 s1, s33, s1
	s_cmp_gt_i32 s1, -1
	s_cbranch_scc0 .LBB0_603
	s_lshl_b32 s2, s1, 7
	s_cbranch_execz .LBB0_604
	s_branch .LBB0_605

; #define PP load_params()
; template <int layer>
; __device__ __forceinline__ void run_layer(LAS unsigned char* lds, const XcdBarrier& xb) {
;     ...
;             xcd_barrier(xb);
;             __syncthreads();
;             { pg8::GemmSched S; S.init(T, 2048, G, blockIdx.x, ws + OFF_Z0, 2048, WOUT, 2048);
;               EpiOut<false, layer == 3> E{PP.x_prompt, PP.x_sample, PP.out, XB, RSS};
;               pg8::gemm_phase(lds, 2048, 2048, 2048, S, E); }
.LBB0_870:
	s_or_b64 exec, exec, s[8:9]
	s_mov_b64 s[0:1], s[92:93]
	s_barrier
	s_barrier
	s_and_b32 s98, s33, 7

; #define PP load_params()
; template <int layer>
; __device__ __forceinline__ void run_layer(LAS unsigned char* lds, const XcdBarrier& xb) {
;     ...
;             { pg8::GemmSched S; S.init(T, 2048, G, blockIdx.x, ws + OFF_Z0, 2048, WOUT, 2048);
;               EpiOut<false, layer == 3> E{PP.x_prompt, PP.x_sample, PP.out, XB, RSS};
;               pg8::gemm_phase(lds, 2048, 2048, 2048, S, E); }
.Lstag1_done:
	s_mov_b64 s[0:1], s[92:93]
	s_mov_b64 s[0:1], s[92:93]
	v_mov_b32_e32 v8, v254
	v_readlane_b32 s0, v255, 24
	v_readlane_b32 s1, v255, 25
	s_and_b64 vcc, exec, s[0:1]
	v_readfirstlane_b32 s0, v8
	s_cbranch_vccnz .LBB0_876
	s_ashr_i32 s1, s33, 31
	s_lshr_b32 s1, s1, 29
	s_add_i32 s1, s33, s1
	s_and_b32 s2, s1, -8
	s_sub_i32 s2, s33, s2
	s_cmp_gt_i32 s2, -1
	s_cbranch_scc0 .LBB0_873
	s_lshl_b32 s4, s2, 7
	s_cbranch_execz .LBB0_874
	s_branch .LBB0_875

; #define PP load_params()
; template <int layer>
; __device__ __forceinline__ void run_layer(LAS unsigned char* lds, const XcdBarrier& xb) {
;     ...
;             xcd_barrier(xb);
;             __syncthreads();
;             { pg8::GemmSched S; S.init(T, 2048, G, blockIdx.x, ws + OFF_Z0, 2048, WOUT, 2048);
;               EpiOut<layer == 0, false> E{PP.x_prompt, PP.x_sample, PP.out, XB, RSS};
;               pg8::gemm_phase(lds, 2048, 2048, 2048, S, E); }
.LBB0_1353:
	s_or_b64 exec, exec, s[8:9]
	s_mov_b64 s[0:1], s[82:83]
	s_barrier
	s_barrier
	s_and_b32 s98, s33, 7

; #define PP load_params()
; template <int layer>
; __device__ __forceinline__ void run_layer(LAS unsigned char* lds, const XcdBarrier& xb) {
;     ...
;             { pg8::GemmSched S; S.init(T, 2048, G, blockIdx.x, ws + OFF_Z0, 2048, WOUT, 2048);
;               EpiOut<layer == 0, false> E{PP.x_prompt, PP.x_sample, PP.out, XB, RSS};
;               pg8::gemm_phase(lds, 2048, 2048, 2048, S, E); }
.Lstag2_done:
	s_mov_b64 s[0:1], s[82:83]
	s_mov_b64 s[0:1], s[82:83]
	v_mov_b32_e32 v8, v254
	v_readlane_b32 s0, v255, 24
	v_readlane_b32 s1, v255, 25
	s_and_b64 vcc, exec, s[0:1]
	v_readfirstlane_b32 s0, v8
	s_cbranch_vccnz .LBB0_1359
	s_ashr_i32 s1, s33, 31
	s_lshr_b32 s1, s1, 29
	s_add_i32 s1, s33, s1
	s_and_b32 s2, s1, -8
	s_sub_i32 s2, s33, s2
	s_cmp_gt_i32 s2, -1
	s_cbranch_scc0 .LBB0_1356
	s_lshl_b32 s4, s2, 7
	s_cbranch_execz .LBB0_1357
	s_branch .LBB0_1358

; #define PP load_params()
; template <int layer>
; __device__ __forceinline__ void run_layer(LAS unsigned char* lds, const XcdBarrier& xb) {
;     ...
;             xcd_barrier(xb);
;             __syncthreads();
;             { pg8::GemmSched S; S.init(T, 2048, G, blockIdx.x, ws + OFF_Z0, 2048, WOUT, 2048);
;               EpiOut<false, layer == 3> E{PP.x_prompt, PP.x_sample, PP.out, XB, RSS};
;               pg8::gemm_phase(lds, 2048, 2048, 2048, S, E); }
.LBB0_1608:
	s_or_b64 exec, exec, s[6:7]
	s_mov_b64 s[0:1], s[82:83]
	s_barrier
	s_barrier
	s_and_b32 s98, s33, 7

; #define PP load_params()
; template <int layer>
; __device__ __forceinline__ void run_layer(LAS unsigned char* lds, const XcdBarrier& xb) {
;     ...
;             { pg8::GemmSched S; S.init(T, 2048, G, blockIdx.x, ws + OFF_Z0, 2048, WOUT, 2048);
;               EpiOut<false, layer == 3> E{PP.x_prompt, PP.x_sample, PP.out, XB, RSS};
;               pg8::gemm_phase(lds, 2048, 2048, 2048, S, E); }
.Lstag3_done:
	s_mov_b64 s[0:1], s[82:83]
	s_nop 0
	v_readlane_b32 s0, v255, 24
	v_readlane_b32 s1, v255, 25
	s_and_b64 vcc, exec, s[0:1]
	v_readfirstlane_b32 s0, v254
	s_cbranch_vccnz .LBB0_1632
	s_ashr_i32 s2, s33, 31
	s_lshr_b32 s1, s2, 29
	s_add_i32 s7, s33, s1
	s_and_b32 s1, s7, -8
	s_sub_i32 s1, s33, s1
	s_cmp_gt_i32 s1, -1
	s_cbranch_scc0 .LBB0_1611
	s_lshl_b32 s6, s1, 7
	s_ashr_i32 s4, s7, 3
	s_cbranch_execz .LBB0_1612
	s_branch .LBB0_1613
